# attention A odd step: third-slice K fragments requested early into the dead -m copies (restored afterwards), counted lgkm waits
# speedup vs baseline: 1.0055x; 1.0055x over previous
; template <bool FIRST> __device__ __forceinline__ void partialSM(f32x16& p0, f32x16& p1, float& m_reg, f32x16& negm, float& alpha) {
;     ...
;   for (int r = 0; r < 16; ++r) p0[r] = __builtin_amdgcn_exp2f(p0[r]);
; }
; __device__ __forceinline__ void finishSM(f32x16& p0, f32x16& p1, float alpha, float& l_reg, bf16x8& pa0, bf16x8& pa1, bf16x8& pa2, bf16x8& pa3) {
; #pragma unroll
;   for (int r = 0; r < 16; ++r) p1[r] = __builtin_amdgcn_exp2f(p1[r]);
;   float ps = 0;
; #pragma unroll
;   for (int r = 0; r < 16; ++r) ps += p0[r];
; #pragma unroll
;   for (int r = 0; r < 16; ++r) ps += p1[r];
;   { auto rr = __builtin_amdgcn_permlane32_swap(__float_as_uint(ps), __float_as_uint(ps), false, false);
;     ps = __uint_as_float(rr[0]) + __uint_as_float(rr[1]); }
;   l_reg = l_reg * alpha + ps;
;     ...
;   ATT_PKN(p0, 0, pa0); ATT_PKN(p0, 8, pa1); ATT_PKN(p1, 0, pa2); ATT_PKN(p1, 8, pa3);
;     ...
; }
; __device__ __forceinline__ void qkt(f32x16& p0, f32x16& p1, const bf16* Ks, const bf16x8* qr, int r32, int hi, int mp, const f32x16& negm) {
; #pragma unroll
;   for (int d0 = 0; d0 < 4; ++d0) { int cb = ((mp * 4 + d0) * 16 + hi * 8) * 2;
;     bf16x8 b0 = *reinterpret_cast<const bf16x8*>((const char*)Ks + KSWZ(r32, cb));
;     bf16x8 b1 = *reinterpret_cast<const bf16x8*>((const char*)Ks + KSWZ(32 + r32, cb));
;     if (d0 == 0) { p0 = __builtin_amdgcn_mfma_f32_32x32x16_bf16(b0, qr[0], negm, 0, 0, 0); p1 = __builtin_amdgcn_mfma_f32_32x32x16_bf16(b1, qr[0], negm, 0, 0, 0); }
;     else { p0 = __builtin_amdgcn_mfma_f32_32x32x16_bf16(b0, qr[d0], p0, 0, 0, 0); p1 = __builtin_amdgcn_mfma_f32_32x32x16_bf16(b1, qr[d0], p1, 0, 0, 0); } }
; }
; __device__ __forceinline__ int v_st(int k, int c) { const int kk = k; return ((kk >> 3) * 4 + (c >> 5)) * 512 + ((kk & 7) * 32 + (c & 31)) * 2; }
; template <int D0> __device__ __forceinline__ void pv_one(f32x16& od, int vb, bf16x8 pa0, bf16x8 pa1, bf16x8 pa2, bf16x8 pa3) {
;   const s16x4 l0 = tr_read<v_rd_off(D0, 0, 0)>(vb), h0 = tr_read<v_rd_off(D0, 0, 1)>(vb), l1 = tr_read<v_rd_off(D0, 1, 0)>(vb), h1 = tr_read<v_rd_off(D0, 1, 1)>(vb);
;   const s16x4 l2 = tr_read<v_rd_off(D0, 2, 0)>(vb), h2 = tr_read<v_rd_off(D0, 2, 1)>(vb), l3 = tr_read<v_rd_off(D0, 3, 0)>(vb), h3 = tr_read<v_rd_off(D0, 3, 1)>(vb);
.LBB0_202:
	v_exp_f32_e32 v211, v128
	v_exp_f32_e32 v213, v129
	v_exp_f32_e32 v214, v130
	v_exp_f32_e32 v217, v131
	v_exp_f32_e32 v232, v132
	v_exp_f32_e32 v235, v133
	v_exp_f32_e32 v236, v134
	v_exp_f32_e32 v239, v135
	v_exp_f32_e32 v212, v136
	v_exp_f32_e32 v215, v137
	v_exp_f32_e32 v216, v138
	v_exp_f32_e32 v233, v139
	v_exp_f32_e32 v234, v140
	v_exp_f32_e32 v237, v141
	v_exp_f32_e32 v238, v142
	v_exp_f32_e32 v240, v143
	s_waitcnt vmcnt(4) lgkmcnt(0)
	s_barrier
	s_add_i32 s10, s39, 0x8000
	s_and_b32 s48, s10, 0x1ffff
	s_add_i32 s10, s48, 0
	v_add_u32_e32 v96, s10, v202
	ds_read_b128 v[242:245], v96 offset:24576
	ds_read_b128 v[96:99], v96 offset:16384
	v_add_u32_e32 v241, s10, v201
	v_exp_f32_e32 v112, v112
	v_exp_f32_e32 v115, v115
	v_exp_f32_e32 v116, v116
	s_waitcnt lgkmcnt(0)
	v_mfma_f32_32x32x16_bf16 v[128:143], v[96:99], v[158:161], v[64:79]
	v_exp_f32_e32 v117, v117
	v_exp_f32_e32 v118, v118
	v_mfma_f32_32x32x16_bf16 v[96:111], v[242:245], v[158:161], v[64:79]
	ds_read_b128 v[242:245], v241 offset:24576
	ds_read_b128 v[246:249], v241 offset:16384
	v_add_u32_e32 v241, s10, v199
	s_nop 4
	ds_read_b128 v[68:71], v241 offset:24576
	ds_read_b128 v[72:75], v241 offset:16384
	v_add_u32_e32 v241, s10, v183
	s_waitcnt lgkmcnt(2)
	v_mfma_f32_32x32x16_bf16 v[128:143], v[246:249], v[154:157], v[128:143]
	v_mfma_f32_32x32x16_bf16 v[96:111], v[242:245], v[154:157], v[96:111]
	ds_read_b128 v[242:245], v241 offset:24576
	ds_read_b128 v[246:249], v241 offset:16384
	s_waitcnt lgkmcnt(2)
	v_mfma_f32_32x32x16_bf16 v[128:143], v[72:75], v[150:153], v[128:143]
	v_mfma_f32_32x32x16_bf16 v[96:111], v[68:71], v[150:153], v[96:111]
	v_mov_b64_e32 v[68:69], v[84:85]
	v_mov_b64_e32 v[70:71], v[86:87]
	v_mov_b64_e32 v[72:73], v[88:89]
	v_mov_b64_e32 v[74:75], v[90:91]
	v_exp_f32_e32 v241, v113
	v_add_f32_e32 v113, 0, v211
	v_add_f32_e32 v113, v213, v113
	v_add_f32_e32 v113, v214, v113
	v_add_f32_e32 v113, v217, v113
	v_add_f32_e32 v113, v232, v113
	v_add_f32_e32 v113, v235, v113
	v_add_f32_e32 v113, v236, v113
	v_add_f32_e32 v113, v239, v113
	v_add_f32_e32 v113, v212, v113
	v_add_f32_e32 v113, v215, v113
	v_add_f32_e32 v113, v216, v113
	v_add_f32_e32 v113, v233, v113
	v_add_f32_e32 v113, v234, v113
	v_add_f32_e32 v113, v237, v113
	s_waitcnt lgkmcnt(0)
	v_mfma_f32_32x32x16_bf16 v[96:111], v[242:245], v[146:149], v[96:111]
	v_exp_f32_e32 v242, v114
	v_add_f32_e32 v113, v238, v113
	v_add_f32_e32 v113, v240, v113
	v_add_f32_e32 v113, v112, v113
	v_add_f32_e32 v113, v241, v113
	v_add_f32_e32 v113, v242, v113
	v_exp_f32_e32 v243, v119
	v_add_f32_e32 v113, v115, v113
	v_exp_f32_e32 v119, v120
	v_add_f32_e32 v113, v116, v113
	v_exp_f32_e32 v120, v121
	v_add_f32_e32 v113, v117, v113
	v_exp_f32_e32 v121, v122
	v_add_f32_e32 v113, v118, v113
	v_exp_f32_e32 v122, v123
	v_add_f32_e32 v113, v243, v113
	v_exp_f32_e32 v123, v124
	v_add_f32_e32 v113, v119, v113
	v_exp_f32_e32 v124, v125
	v_add_f32_e32 v113, v120, v113
	v_mfma_f32_32x32x16_bf16 v[128:143], v[246:249], v[146:149], v[128:143]
	v_exp_f32_e32 v125, v126
	v_add_f32_e32 v113, v121, v113
	v_exp_f32_e32 v126, v127
	v_add_f32_e32 v113, v122, v113
	v_add_f32_e32 v113, v123, v113
	v_add_f32_e32 v113, v124, v113
	v_add_f32_e32 v113, v125, v113
	v_add_f32_e32 v113, v126, v113
	v_mov_b32_e32 v114, v113
	s_nop 1
	v_permlane32_swap_b32_e32 v113, v114
	v_cvt_pk_bf16_f32 v250, v211, v213
	v_cvt_pk_bf16_f32 v251, v214, v217
	v_cvt_pk_bf16_f32 v252, v232, v235
	v_cvt_pk_bf16_f32 v253, v236, v239
	v_cvt_pk_bf16_f32 v212, v212, v215
	v_cvt_pk_bf16_f32 v213, v216, v233
	v_cvt_pk_bf16_f32 v214, v234, v237
	v_cvt_pk_bf16_f32 v215, v238, v240
	v_cvt_pk_bf16_f32 v232, v112, v241
	v_cvt_pk_bf16_f32 v233, v242, v115
	v_cvt_pk_bf16_f32 v234, v116, v117
	v_cvt_pk_bf16_f32 v235, v118, v243
	v_cvt_pk_bf16_f32 v116, v119, v120
	v_cvt_pk_bf16_f32 v117, v121, v122
	v_cvt_pk_bf16_f32 v118, v123, v124
	v_cvt_pk_bf16_f32 v119, v125, v126
	v_add_u32_e32 v112, s39, v205
	ds_read_b64_tr_b16 v[120:121], v112 offset:0
	ds_read_b64_tr_b16 v[122:123], v112 offset:0x800
	ds_read_b64_tr_b16 v[124:125], v112 offset:0x1000
	ds_read_b64_tr_b16 v[126:127], v112 offset:0x1800
	ds_read_b64_tr_b16 v[236:237], v112 offset:0x2000
	ds_read_b64_tr_b16 v[238:239], v112 offset:0x2800
	ds_read_b64_tr_b16 v[240:241], v112 offset:0x3000
	ds_read_b64_tr_b16 v[242:243], v112 offset:0x3800
	s_cmp_gt_u32 s44, 60
	s_cselect_b64 s[52:53], -1, 0
	s_and_b64 vcc, exec, s[52:53]
	s_cbranch_vccnz .LBB0_204
	s_add_i32 s10, s56, 0x8000
	s_and_b32 s10, s10, 0x1ffff
	s_add_i32 s12, s21, s10
	v_lshl_add_u64 v[174:175], v[174:175], 0, s[68:69]
	s_add_i32 m0, s12, 0x4000
	s_mov_b64 s[10:11], 0x4040000
	global_load_lds_dwordx4 v[174:175], off
	v_lshl_add_u64 v[174:175], v[172:173], 0, s[10:11]
	s_mov_b32 m0, s12
	s_mov_b64 s[10:11], 0x4040080
	global_load_lds_dwordx4 v[174:175], off
	v_lshl_add_u64 v[174:175], v[176:177], 0, s[68:69]
	s_add_i32 m0, s12, 0x4400
	v_lshl_add_u64 v[172:173], v[172:173], 0, s[10:11]
	global_load_lds_dwordx4 v[174:175], off
	s_add_i32 m0, s12, 0x400
	s_nop 0
	global_load_lds_dwordx4 v[172:173], off
